# RESID epilogue: row-group loads prefetched two groups ahead into spare registers via SGPR-base addressing, counted waits
# baseline (speedup 1.0000x reference)
; template <int EPI>
; __device__ __forceinline__ void gemm_epilogue(const f32x4 (&acc)[2][2][4][2], const Unit& u, int wr, int wc, int fr, int fq,
;                                               const EpiArgs& ea, const float (&rs_pre)[2][4]) {
;     ...
;     EPI_LOAD_ROW(0, hc, lc, pc);
; #pragma unroll
;     for (int it = 0; it < 8; ++it) {
;       const int ai = it >> 2, m = it & 3;
;       if (it + 1 < 8) EPI_LOAD_ROW(it + 1, hn, ln_, pq);
;       const int row = row0 + ai * 128 + m * 16;
;       float sq = 0.f;
; #pragma unroll
;       for (int bj = 0; bj < 2; ++bj) {
;         const size_t idx = (size_t)row * 1024 + lcp + bj * 32;
;         const uint32_t hw[4] = {hc[bj].x, hc[bj].y, hc[bj].z, hc[bj].w};
;         const uint32_t lw[4] = {lc[bj].x, lc[bj].y, lc[bj].z, lc[bj].w};
;         const uint32_t pw[4] = {pc[bj].x, pc[bj].y, pc[bj].z, pc[bj].w};
;         uint32_t ho[4], lo_[4];
; #pragma unroll
;         for (int n = 0; n < 2; ++n) {
;           f32x4 xv;
;           xv[0] = __uint_as_float(hw[2 * n] << 16) + __uint_as_float(lw[2 * n] << 16);
;           xv[1] = __uint_as_float(hw[2 * n] & 0xffff0000u) + __uint_as_float(lw[2 * n] & 0xffff0000u);
;           xv[2] = __uint_as_float(hw[2 * n + 1] << 16) + __uint_as_float(lw[2 * n + 1] << 16);
;           xv[3] = __uint_as_float(hw[2 * n + 1] & 0xffff0000u) + __uint_as_float(lw[2 * n + 1] & 0xffff0000u);
;           const f32x4 a = acc[ai][bj][m][n];
;           f32x4 v;
;           if constexpr (EPI == EPI_PLEGATE) {
;             const float rs = rsr[ai][m], rpe = rper[ai][m];
;             const float pv[4] = {__uint_as_float(pw[2 * n] << 16), __uint_as_float(pw[2 * n] & 0xffff0000u),
;                                  __uint_as_float(pw[2 * n + 1] << 16), __uint_as_float(pw[2 * n + 1] & 0xffff0000u)};
; #pragma unroll
;             for (int i = 0; i < 4; ++i) v[i] = xv[i] + sigmoidf_(a[i] * rs) * (pv[i] * rpe);
;           } else {
;             v = xv + a * ea.alpha;
;           }
;           const uint2 hnew = pack4(v);
;           ho[2 * n] = hnew.x; ho[2 * n + 1] = hnew.y;
;           if (ea.xf32_out) {
;             *reinterpret_cast<f32x4*>(ea.xf32_out + idx + 4 * n) = v;
;           } else {
;             f32x4 r;
;             r[0] = v[0] - __uint_as_float(hnew.x << 16);
;             r[1] = v[1] - __uint_as_float(hnew.x & 0xffff0000u);
.LBB0_869:
	v_lshl_add_u32 v168, s96, 8, v174
	v_lshl_add_u32 v166, s66, 8, v176
	v_lshlrev_b32_e32 v246, 11, v168
	v_lshl_add_u32 v246, v166, 1, v246
	v_ashrrev_i32_e32 v169, 31, v168
	v_lshlrev_b64 v[130:131], 10, v[168:169]
	v_ashrrev_i32_e32 v167, 31, v166
	v_lshl_add_u64 v[130:131], v[130:131], 0, v[166:167]
	v_lshlrev_b64 v[172:173], 1, v[130:131]
	v_lshl_add_u64 v[130:131], s[68:69], 0, v[172:173]
	v_lshl_add_u64 v[132:133], s[88:89], 0, v[172:173]
	global_load_dwordx4 v[154:157], v[130:131], off
	global_load_dwordx4 v[178:181], v[132:133], off
	global_load_dwordx4 v[146:149], v[130:131], off offset:64
	global_load_dwordx4 v[150:153], v[132:133], off offset:64
	v_or_b32_e32 v130, 16, v168
	v_ashrrev_i32_e32 v131, 31, v130
	v_lshlrev_b64 v[130:131], 10, v[130:131]
	v_lshl_add_u64 v[130:131], v[130:131], 0, v[166:167]
	v_lshlrev_b64 v[170:171], 1, v[130:131]
	v_lshl_add_u64 v[130:131], s[68:69], 0, v[170:171]
	v_lshl_add_u64 v[134:135], s[88:89], 0, v[170:171]
	global_load_dwordx4 v[138:141], v[130:131], off
	global_load_dwordx4 v[142:145], v[134:135], off
	s_nop 0
	global_load_dwordx4 v[130:133], v[130:131], off offset:64
	s_nop 0
	global_load_dwordx4 v[134:137], v[134:135], off offset:64
	v_add_u32_e32 v247, 0x10000, v246
	global_load_dwordx4 v[194:197], v247, s[68:69]
	global_load_dwordx4 v[198:201], v247, s[88:89]
	global_load_dwordx4 v[202:205], v247, s[68:69] offset:64
	global_load_dwordx4 v[234:237], v247, s[88:89] offset:64
	v_add_u32_e32 v247, 0x18000, v246
	global_load_dwordx4 v[238:241], v247, s[68:69]
	global_load_dwordx4 v[242:245], v247, s[88:89]
	global_load_dwordx4 v[210:213], v247, s[68:69] offset:64
	global_load_dwordx4 v[214:217], v247, s[88:89] offset:64
	s_waitcnt vmcnt(12)
	v_lshlrev_b32_e32 v186, 16, v154
	v_lshlrev_b32_e32 v188, 16, v178
	v_and_b32_e32 v187, 0xffff0000, v154
	v_and_b32_e32 v189, 0xffff0000, v178
	v_lshlrev_b32_e32 v154, 16, v155
	v_lshlrev_b32_e32 v178, 16, v179
	v_and_b32_e32 v155, 0xffff0000, v155
	v_and_b32_e32 v179, 0xffff0000, v179
	v_pk_add_f32 v[186:187], v[186:187], v[188:189]
	v_pk_add_f32 v[154:155], v[154:155], v[178:179]
	v_pk_fma_f32 v[178:179], s[6:7], v[126:127], v[186:187]
	v_pk_fma_f32 v[128:129], s[60:61], v[128:129], v[154:155]
	v_cvt_pk_bf16_f32 v154, v178, v179
	s_nop 0
	v_cvt_pk_bf16_f32 v155, v128, v129
	v_lshlrev_b32_e32 v126, 16, v154
	v_and_b32_e32 v127, 0xffff0000, v154
	v_lshlrev_b32_e32 v182, 16, v155
	v_sub_f32_e32 v126, v178, v126
	v_sub_f32_e32 v127, v179, v127
	v_sub_f32_e32 v182, v128, v182
	v_and_b32_e32 v185, 0xffff0000, v155
	v_sub_f32_e32 v185, v129, v185
	v_cvt_pk_bf16_f32 v126, v126, v127
	v_cvt_pk_bf16_f32 v127, v182, v185
	v_mul_f32_e32 v182, v179, v179
	v_fmac_f32_e32 v182, v178, v178
	v_fmac_f32_e32 v182, v128, v128
	v_fmac_f32_e32 v182, v129, v129
	v_lshlrev_b32_e32 v128, 16, v156
	v_lshlrev_b32_e32 v178, 16, v180
	v_and_b32_e32 v129, 0xffff0000, v156
	v_and_b32_e32 v179, 0xffff0000, v180
	v_lshlrev_b32_e32 v156, 16, v157
	v_lshlrev_b32_e32 v180, 16, v181
	v_and_b32_e32 v157, 0xffff0000, v157
	v_and_b32_e32 v181, 0xffff0000, v181
	v_pk_add_f32 v[128:129], v[128:129], v[178:179]
	v_pk_add_f32 v[156:157], v[156:157], v[180:181]
	v_pk_fma_f32 v[122:123], s[6:7], v[122:123], v[128:129]
	v_pk_fma_f32 v[124:125], s[60:61], v[124:125], v[156:157]
	v_cvt_pk_bf16_f32 v156, v122, v123
	s_nop 0
	v_and_b32_e32 v129, 0xffff0000, v156
	v_sub_f32_e32 v129, v123, v129
	v_mul_f32_e32 v123, v123, v123
	v_fmac_f32_e32 v123, v122, v122
	v_cvt_pk_bf16_f32 v157, v124, v125
	v_lshlrev_b32_e32 v128, 16, v156
	v_lshlrev_b32_e32 v178, 16, v157
	v_fmac_f32_e32 v123, v124, v124
	v_sub_f32_e32 v128, v122, v128
	v_sub_f32_e32 v178, v124, v178
	v_and_b32_e32 v179, 0xffff0000, v157
	v_fmac_f32_e32 v123, v125, v125
	v_sub_f32_e32 v179, v125, v179
	v_cvt_pk_bf16_f32 v128, v128, v129
	v_cvt_pk_bf16_f32 v129, v178, v179
	v_add_f32_e32 v178, v182, v123
	v_lshl_add_u64 v[122:123], s[46:47], 0, v[172:173]
	v_lshl_add_u64 v[124:125], s[70:71], 0, v[172:173]
	global_store_dwordx4 v[122:123], v[154:157], off
	global_store_dwordx4 v[124:125], v[126:129], off
	s_nop 1
	v_lshlrev_b32_e32 v126, 16, v146
	v_lshlrev_b32_e32 v128, 16, v150
	v_and_b32_e32 v127, 0xffff0000, v146
	v_and_b32_e32 v129, 0xffff0000, v150
	v_lshlrev_b32_e32 v146, 16, v147
	v_lshlrev_b32_e32 v150, 16, v151
	v_and_b32_e32 v147, 0xffff0000, v147
	v_and_b32_e32 v151, 0xffff0000, v151
	v_pk_add_f32 v[126:127], v[126:127], v[128:129]
	v_pk_add_f32 v[128:129], v[146:147], v[150:151]
	s_nop 0
	v_pk_fma_f32 v[120:121], s[60:61], v[120:121], v[128:129]
	v_pk_fma_f32 v[128:129], s[6:7], v[118:119], v[126:127]
	v_cvt_pk_bf16_f32 v119, v120, v121
	s_nop 0
	v_cvt_pk_bf16_f32 v118, v128, v129
	v_lshlrev_b32_e32 v146, 16, v119
	v_and_b32_e32 v127, 0xffff0000, v118
	v_sub_f32_e32 v127, v129, v127
	v_mul_f32_e32 v129, v129, v129
	v_fmac_f32_e32 v129, v128, v128
	v_lshlrev_b32_e32 v126, 16, v118
	v_and_b32_e32 v147, 0xffff0000, v119
	v_fmac_f32_e32 v129, v120, v120
	v_sub_f32_e32 v126, v128, v126
	v_sub_f32_e32 v146, v120, v146
	v_sub_f32_e32 v147, v121, v147
	v_fmac_f32_e32 v129, v121, v121
	v_cvt_pk_bf16_f32 v126, v126, v127
	v_cvt_pk_bf16_f32 v127, v146, v147
	v_add_f32_e32 v150, v178, v129
	v_lshlrev_b32_e32 v120, 16, v148
	v_lshlrev_b32_e32 v128, 16, v152
	v_and_b32_e32 v121, 0xffff0000, v148
	v_and_b32_e32 v129, 0xffff0000, v152
	v_lshlrev_b32_e32 v146, 16, v149
	v_lshlrev_b32_e32 v148, 16, v153
	v_and_b32_e32 v147, 0xffff0000, v149
	v_and_b32_e32 v149, 0xffff0000, v153
	v_pk_add_f32 v[120:121], v[120:121], v[128:129]
	v_pk_add_f32 v[128:129], v[146:147], v[148:149]
	v_pk_fma_f32 v[114:115], s[6:7], v[114:115], v[120:121]
	v_pk_fma_f32 v[116:117], s[60:61], v[116:117], v[128:129]
	v_cvt_pk_bf16_f32 v120, v114, v115
	s_nop 0
	v_and_b32_e32 v129, 0xffff0000, v120
	v_sub_f32_e32 v129, v115, v129
	v_mul_f32_e32 v115, v115, v115
	v_fmac_f32_e32 v115, v114, v114
	v_fmac_f32_e32 v115, v116, v116
	v_lshlrev_b32_e32 v128, 16, v120
	v_fmac_f32_e32 v115, v117, v117
	v_sub_f32_e32 v128, v114, v128
	v_add_f32_e32 v114, v150, v115
	v_mov_b32_e32 v115, v114
	s_nop 1
	v_permlane16_swap_b32_e32 v114, v115
	v_cvt_pk_bf16_f32 v121, v116, v117
	v_add_f32_e32 v114, v114, v115
	v_lshlrev_b32_e32 v146, 16, v121
	v_and_b32_e32 v147, 0xffff0000, v121
	v_sub_f32_e32 v146, v116, v146
	v_sub_f32_e32 v147, v117, v147
	v_mov_b32_e32 v115, v114
	v_cvt_pk_bf16_f32 v128, v128, v129
	v_cvt_pk_bf16_f32 v129, v146, v147
	s_nop 1
	v_permlane32_swap_b32_e32 v114, v115
	v_lshl_add_u64 v[146:147], v[168:169], 2, s[62:63]
	global_store_dwordx4 v[122:123], v[118:121], off offset:64
	global_store_dwordx4 v[124:125], v[126:129], off offset:64
	s_and_saveexec_b64 s[36:37], s[0:1]
	s_cbranch_execz .LBB0_871
	v_add_f32_e32 v114, v114, v115
	global_atomic_add_f32 v[146:147], v114, off
; template <int EPI>
; __device__ __forceinline__ void gemm_epilogue(const f32x4 (&acc)[2][2][4][2], const Unit& u, int wr, int wc, int fr, int fq,
;                                               const EpiArgs& ea, const float (&rs_pre)[2][4]) {
;     ...
;       const int row = row0 + ai * 128 + m * 16;
;       float sq = 0.f;
; #pragma unroll
;       for (int bj = 0; bj < 2; ++bj) {
;         const size_t idx = (size_t)row * 1024 + lcp + bj * 32;
;         const uint32_t hw[4] = {hc[bj].x, hc[bj].y, hc[bj].z, hc[bj].w};
;         const uint32_t lw[4] = {lc[bj].x, lc[bj].y, lc[bj].z, lc[bj].w};
;         const uint32_t pw[4] = {pc[bj].x, pc[bj].y, pc[bj].z, pc[bj].w};
;         uint32_t ho[4], lo_[4];
; #pragma unroll
;         for (int n = 0; n < 2; ++n) {
;           f32x4 xv;
;           xv[0] = __uint_as_float(hw[2 * n] << 16) + __uint_as_float(lw[2 * n] << 16);
;           xv[1] = __uint_as_float(hw[2 * n] & 0xffff0000u) + __uint_as_float(lw[2 * n] & 0xffff0000u);
;           xv[2] = __uint_as_float(hw[2 * n + 1] << 16) + __uint_as_float(lw[2 * n + 1] << 16);
;           xv[3] = __uint_as_float(hw[2 * n + 1] & 0xffff0000u) + __uint_as_float(lw[2 * n + 1] & 0xffff0000u);
;           const f32x4 a = acc[ai][bj][m][n];
;           f32x4 v;
;           if constexpr (EPI == EPI_PLEGATE) {
;             const float rs = rsr[ai][m], rpe = rper[ai][m];
;             const float pv[4] = {__uint_as_float(pw[2 * n] << 16), __uint_as_float(pw[2 * n] & 0xffff0000u),
;                                  __uint_as_float(pw[2 * n + 1] << 16), __uint_as_float(pw[2 * n + 1] & 0xffff0000u)};
; #pragma unroll
;             for (int i = 0; i < 4; ++i) v[i] = xv[i] + sigmoidf_(a[i] * rs) * (pv[i] * rpe);
;           } else {
;             v = xv + a * ea.alpha;
;           }
;           const uint2 hnew = pack4(v);
;           ho[2 * n] = hnew.x; ho[2 * n + 1] = hnew.y;
;           if (ea.xf32_out) {
;             *reinterpret_cast<f32x4*>(ea.xf32_out + idx + 4 * n) = v;
;           } else {
;             f32x4 r;
;             r[0] = v[0] - __uint_as_float(hnew.x << 16);
;             r[1] = v[1] - __uint_as_float(hnew.x & 0xffff0000u);
;             r[2] = v[2] - __uint_as_float(hnew.y << 16);
;             r[3] = v[3] - __uint_as_float(hnew.y & 0xffff0000u);
;             const uint2 lnew = pack4(r);
;             lo_[2 * n] = lnew.x; lo_[2 * n + 1] = lnew.y;
;           }
.LBB0_871:
	s_waitcnt vmcnt(12)
	s_or_b64 exec, exec, s[36:37]
	v_or_b32_e32 v114, 32, v168
	v_ashrrev_i32_e32 v115, 31, v114
	v_lshlrev_b64 v[114:115], 10, v[114:115]
	v_lshl_add_u64 v[114:115], v[114:115], 0, v[166:167]
	v_lshlrev_b64 v[148:149], 1, v[114:115]
	v_lshl_add_u64 v[114:115], s[68:69], 0, v[148:149]
	v_lshl_add_u64 v[118:119], s[88:89], 0, v[148:149]
	s_nop 0
	s_nop 0
	s_nop 0
	v_lshlrev_b32_e32 v150, 16, v138
	v_lshlrev_b32_e32 v152, 16, v142
	v_and_b32_e32 v151, 0xffff0000, v138
	v_and_b32_e32 v153, 0xffff0000, v142
	v_lshlrev_b32_e32 v138, 16, v139
	v_lshlrev_b32_e32 v142, 16, v143
	v_and_b32_e32 v139, 0xffff0000, v139
	v_and_b32_e32 v143, 0xffff0000, v143
	v_pk_add_f32 v[150:151], v[150:151], v[152:153]
	v_pk_add_f32 v[138:139], v[138:139], v[142:143]
	v_pk_fma_f32 v[142:143], s[6:7], v[108:109], v[150:151]
	v_pk_fma_f32 v[110:111], s[60:61], v[110:111], v[138:139]
	v_cvt_pk_bf16_f32 v108, v142, v143
	s_nop 0
	v_cvt_pk_bf16_f32 v109, v110, v111
	v_lshlrev_b32_e32 v138, 16, v108
	v_and_b32_e32 v139, 0xffff0000, v108
	v_lshlrev_b32_e32 v150, 16, v109
	v_sub_f32_e32 v138, v142, v138
	v_sub_f32_e32 v139, v143, v139
	v_sub_f32_e32 v150, v110, v150
	v_and_b32_e32 v151, 0xffff0000, v109
	v_sub_f32_e32 v151, v111, v151
	v_cvt_pk_bf16_f32 v138, v138, v139
	v_cvt_pk_bf16_f32 v139, v150, v151
	v_mul_f32_e32 v150, v143, v143
	v_fmac_f32_e32 v150, v142, v142
	v_fmac_f32_e32 v150, v110, v110
	v_fmac_f32_e32 v150, v111, v111
	v_lshlrev_b32_e32 v110, 16, v140
	v_lshlrev_b32_e32 v142, 16, v144
	v_and_b32_e32 v111, 0xffff0000, v140
	v_and_b32_e32 v143, 0xffff0000, v144
	v_lshlrev_b32_e32 v140, 16, v141
	v_lshlrev_b32_e32 v144, 16, v145
	v_and_b32_e32 v141, 0xffff0000, v141
	v_and_b32_e32 v145, 0xffff0000, v145
	v_pk_add_f32 v[110:111], v[110:111], v[142:143]
	v_pk_add_f32 v[140:141], v[140:141], v[144:145]
	v_pk_fma_f32 v[104:105], s[6:7], v[104:105], v[110:111]
	v_pk_fma_f32 v[106:107], s[60:61], v[106:107], v[140:141]
	v_cvt_pk_bf16_f32 v110, v104, v105
	s_nop 0
	v_and_b32_e32 v141, 0xffff0000, v110
	v_sub_f32_e32 v141, v105, v141
	v_mul_f32_e32 v105, v105, v105
	v_cvt_pk_bf16_f32 v111, v106, v107
	v_lshlrev_b32_e32 v140, 16, v110
	v_lshlrev_b32_e32 v142, 16, v111
	v_and_b32_e32 v143, 0xffff0000, v111
	v_fmac_f32_e32 v105, v104, v104
	v_sub_f32_e32 v140, v104, v140
	v_sub_f32_e32 v142, v106, v142
	v_sub_f32_e32 v143, v107, v143
	v_fmac_f32_e32 v105, v106, v106
	v_cvt_pk_bf16_f32 v140, v140, v141
	v_cvt_pk_bf16_f32 v141, v142, v143
	v_fmac_f32_e32 v105, v107, v107
	v_lshl_add_u64 v[142:143], s[46:47], 0, v[170:171]
	v_add_f32_e32 v144, v150, v105
	global_store_dwordx4 v[142:143], v[108:111], off
	v_lshlrev_b32_e32 v104, 16, v130
	v_lshlrev_b32_e32 v106, 16, v134
	v_and_b32_e32 v105, 0xffff0000, v130
	v_and_b32_e32 v107, 0xffff0000, v134
	v_lshlrev_b32_e32 v110, 16, v131
	v_lshlrev_b32_e32 v130, 16, v135
	v_and_b32_e32 v111, 0xffff0000, v131
	v_and_b32_e32 v131, 0xffff0000, v135
	v_pk_add_f32 v[104:105], v[104:105], v[106:107]
	v_pk_add_f32 v[106:107], v[110:111], v[130:131]
	v_lshlrev_b32_e32 v130, 16, v137
	v_pk_fma_f32 v[102:103], s[60:61], v[102:103], v[106:107]
	v_pk_fma_f32 v[106:107], s[6:7], v[100:101], v[104:105]
	v_cvt_pk_bf16_f32 v101, v102, v103
	v_and_b32_e32 v131, 0xffff0000, v137
	v_cvt_pk_bf16_f32 v100, v106, v107
	v_lshlrev_b32_e32 v110, 16, v101
	v_and_b32_e32 v105, 0xffff0000, v100
	v_sub_f32_e32 v105, v107, v105
	v_mul_f32_e32 v107, v107, v107
	v_fmac_f32_e32 v107, v106, v106
	v_lshlrev_b32_e32 v104, 16, v100
	v_and_b32_e32 v111, 0xffff0000, v101
	v_fmac_f32_e32 v107, v102, v102
	v_sub_f32_e32 v104, v106, v104
	v_sub_f32_e32 v110, v102, v110
	v_sub_f32_e32 v111, v103, v111
	v_fmac_f32_e32 v107, v103, v103
	v_cvt_pk_bf16_f32 v104, v104, v105
	v_cvt_pk_bf16_f32 v105, v110, v111
	v_add_f32_e32 v134, v144, v107
	v_lshlrev_b32_e32 v102, 16, v132
	v_lshlrev_b32_e32 v106, 16, v136
	v_and_b32_e32 v103, 0xffff0000, v132
	v_and_b32_e32 v107, 0xffff0000, v136
	v_lshlrev_b32_e32 v110, 16, v133
	v_and_b32_e32 v111, 0xffff0000, v133
	v_pk_add_f32 v[102:103], v[102:103], v[106:107]
	v_pk_add_f32 v[106:107], v[110:111], v[130:131]
	v_pk_fma_f32 v[96:97], s[6:7], v[96:97], v[102:103]
	v_pk_fma_f32 v[98:99], s[60:61], v[98:99], v[106:107]
	v_cvt_pk_bf16_f32 v102, v96, v97
	v_lshl_add_u64 v[108:109], s[70:71], 0, v[170:171]
	v_and_b32_e32 v107, 0xffff0000, v102
	v_sub_f32_e32 v107, v97, v107
	v_mul_f32_e32 v97, v97, v97
	v_fmac_f32_e32 v97, v96, v96
	v_fmac_f32_e32 v97, v98, v98
	v_lshlrev_b32_e32 v106, 16, v102
	v_fmac_f32_e32 v97, v99, v99
	v_sub_f32_e32 v106, v96, v106
	v_add_f32_e32 v96, v134, v97
	v_mov_b32_e32 v97, v96
	s_nop 1
	v_permlane16_swap_b32_e32 v96, v97
	v_add_f32_e32 v96, v96, v97
	v_mov_b32_e32 v97, v96
	v_cvt_pk_bf16_f32 v103, v98, v99
	s_nop 1
	v_permlane32_swap_b32_e32 v96, v97
	v_lshlrev_b32_e32 v110, 16, v103
	v_and_b32_e32 v111, 0xffff0000, v103
	global_store_dwordx4 v[108:109], v[138:141], off
	v_sub_f32_e32 v110, v98, v110
	v_sub_f32_e32 v111, v99, v111
	v_cvt_pk_bf16_f32 v106, v106, v107
	v_cvt_pk_bf16_f32 v107, v110, v111
	global_store_dwordx4 v[142:143], v[100:103], off offset:64
	global_store_dwordx4 v[108:109], v[104:107], off offset:64
	s_and_saveexec_b64 s[36:37], s[0:1]
	s_cbranch_execz .LBB0_873
	v_add_f32_e32 v96, v96, v97
	global_atomic_add_f32 v[146:147], v96, off offset:64
; template <int EPI>
; __device__ __forceinline__ void gemm_epilogue(const f32x4 (&acc)[2][2][4][2], const Unit& u, int wr, int wc, int fr, int fq,
;                                               const EpiArgs& ea, const float (&rs_pre)[2][4]) {
;     ...
;       const int row = row0 + ai * 128 + m * 16;
;       float sq = 0.f;
; #pragma unroll
;       for (int bj = 0; bj < 2; ++bj) {
;         const size_t idx = (size_t)row * 1024 + lcp + bj * 32;
;         const uint32_t hw[4] = {hc[bj].x, hc[bj].y, hc[bj].z, hc[bj].w};
;         const uint32_t lw[4] = {lc[bj].x, lc[bj].y, lc[bj].z, lc[bj].w};
;         const uint32_t pw[4] = {pc[bj].x, pc[bj].y, pc[bj].z, pc[bj].w};
;         uint32_t ho[4], lo_[4];
; #pragma unroll
;         for (int n = 0; n < 2; ++n) {
;           f32x4 xv;
;           xv[0] = __uint_as_float(hw[2 * n] << 16) + __uint_as_float(lw[2 * n] << 16);
;           xv[1] = __uint_as_float(hw[2 * n] & 0xffff0000u) + __uint_as_float(lw[2 * n] & 0xffff0000u);
;           xv[2] = __uint_as_float(hw[2 * n + 1] << 16) + __uint_as_float(lw[2 * n + 1] << 16);
;           xv[3] = __uint_as_float(hw[2 * n + 1] & 0xffff0000u) + __uint_as_float(lw[2 * n + 1] & 0xffff0000u);
;           const f32x4 a = acc[ai][bj][m][n];
;           f32x4 v;
;           if constexpr (EPI == EPI_PLEGATE) {
;             const float rs = rsr[ai][m], rpe = rper[ai][m];
;             const float pv[4] = {__uint_as_float(pw[2 * n] << 16), __uint_as_float(pw[2 * n] & 0xffff0000u),
;                                  __uint_as_float(pw[2 * n + 1] << 16), __uint_as_float(pw[2 * n + 1] & 0xffff0000u)};
; #pragma unroll
;             for (int i = 0; i < 4; ++i) v[i] = xv[i] + sigmoidf_(a[i] * rs) * (pv[i] * rpe);
;           } else {
;             v = xv + a * ea.alpha;
;           }
;           const uint2 hnew = pack4(v);
;           ho[2 * n] = hnew.x; ho[2 * n + 1] = hnew.y;
;           if (ea.xf32_out) {
;             *reinterpret_cast<f32x4*>(ea.xf32_out + idx + 4 * n) = v;
;           } else {
;             f32x4 r;
;             r[0] = v[0] - __uint_as_float(hnew.x << 16);
;             r[1] = v[1] - __uint_as_float(hnew.x & 0xffff0000u);
;             r[2] = v[2] - __uint_as_float(hnew.y << 16);
;             r[3] = v[3] - __uint_as_float(hnew.y & 0xffff0000u);
;             const uint2 lnew = pack4(r);
;             lo_[2 * n] = lnew.x; lo_[2 * n + 1] = lnew.y;
;           }
.LBB0_873:
	s_waitcnt vmcnt(12)
	s_or_b64 exec, exec, s[36:37]
	v_or_b32_e32 v96, 48, v168
	v_ashrrev_i32_e32 v97, 31, v96
	v_lshlrev_b64 v[96:97], 10, v[96:97]
	v_lshl_add_u64 v[96:97], v[96:97], 0, v[166:167]
	v_lshlrev_b64 v[130:131], 1, v[96:97]
	v_lshl_add_u64 v[96:97], s[68:69], 0, v[130:131]
	v_lshl_add_u64 v[100:101], s[88:89], 0, v[130:131]
	s_nop 0
	s_nop 0
	s_nop 0
	v_lshlrev_b32_e32 v132, 16, v194
	v_lshlrev_b32_e32 v134, 16, v198
	v_and_b32_e32 v133, 0xffff0000, v194
	v_and_b32_e32 v135, 0xffff0000, v198
	v_lshlrev_b32_e32 v122, 16, v195
	v_lshlrev_b32_e32 v126, 16, v199
	v_and_b32_e32 v123, 0xffff0000, v195
	v_and_b32_e32 v127, 0xffff0000, v199
	v_pk_add_f32 v[132:133], v[132:133], v[134:135]
	v_pk_add_f32 v[122:123], v[122:123], v[126:127]
	v_pk_fma_f32 v[126:127], s[6:7], v[92:93], v[132:133]
	v_pk_fma_f32 v[94:95], s[60:61], v[94:95], v[122:123]
	v_cvt_pk_bf16_f32 v92, v126, v127
	s_nop 0
	v_cvt_pk_bf16_f32 v93, v94, v95
	v_lshlrev_b32_e32 v122, 16, v92
	v_and_b32_e32 v123, 0xffff0000, v92
	v_lshlrev_b32_e32 v132, 16, v93
	v_sub_f32_e32 v122, v126, v122
	v_sub_f32_e32 v123, v127, v123
	v_sub_f32_e32 v132, v94, v132
	v_and_b32_e32 v133, 0xffff0000, v93
	v_sub_f32_e32 v133, v95, v133
	v_cvt_pk_bf16_f32 v122, v122, v123
	v_cvt_pk_bf16_f32 v123, v132, v133
	v_mul_f32_e32 v132, v127, v127
	v_fmac_f32_e32 v132, v126, v126
	v_fmac_f32_e32 v132, v94, v94
	v_fmac_f32_e32 v132, v95, v95
	v_lshlrev_b32_e32 v94, 16, v196
	v_lshlrev_b32_e32 v126, 16, v200
	v_and_b32_e32 v95, 0xffff0000, v196
	v_and_b32_e32 v127, 0xffff0000, v200
	v_lshlrev_b32_e32 v124, 16, v197
	v_lshlrev_b32_e32 v128, 16, v201
	v_and_b32_e32 v125, 0xffff0000, v197
	v_and_b32_e32 v129, 0xffff0000, v201
	v_pk_add_f32 v[94:95], v[94:95], v[126:127]
	v_pk_add_f32 v[124:125], v[124:125], v[128:129]
	v_pk_fma_f32 v[88:89], s[6:7], v[88:89], v[94:95]
	v_pk_fma_f32 v[90:91], s[60:61], v[90:91], v[124:125]
	v_cvt_pk_bf16_f32 v94, v88, v89
	s_nop 0
	v_and_b32_e32 v125, 0xffff0000, v94
	v_sub_f32_e32 v125, v89, v125
	v_mul_f32_e32 v89, v89, v89
	v_cvt_pk_bf16_f32 v95, v90, v91
	v_lshlrev_b32_e32 v124, 16, v94
	v_lshlrev_b32_e32 v126, 16, v95
	v_and_b32_e32 v127, 0xffff0000, v95
	v_fmac_f32_e32 v89, v88, v88
	v_sub_f32_e32 v124, v88, v124
	v_sub_f32_e32 v126, v90, v126
	v_sub_f32_e32 v127, v91, v127
	v_fmac_f32_e32 v89, v90, v90
	v_cvt_pk_bf16_f32 v124, v124, v125
	v_cvt_pk_bf16_f32 v125, v126, v127
	v_fmac_f32_e32 v89, v91, v91
	v_lshl_add_u64 v[126:127], s[46:47], 0, v[148:149]
	v_add_f32_e32 v128, v132, v89
	global_store_dwordx4 v[126:127], v[92:95], off
	v_lshlrev_b32_e32 v88, 16, v202
	v_lshlrev_b32_e32 v90, 16, v234
	v_and_b32_e32 v89, 0xffff0000, v202
	v_and_b32_e32 v91, 0xffff0000, v234
	v_lshlrev_b32_e32 v94, 16, v203
	v_lshlrev_b32_e32 v114, 16, v235
	v_and_b32_e32 v95, 0xffff0000, v203
	v_and_b32_e32 v115, 0xffff0000, v235
	v_pk_add_f32 v[88:89], v[88:89], v[90:91]
	v_pk_add_f32 v[90:91], v[94:95], v[114:115]
	v_lshlrev_b32_e32 v114, 16, v237
	v_pk_fma_f32 v[86:87], s[60:61], v[86:87], v[90:91]
	v_pk_fma_f32 v[90:91], s[6:7], v[84:85], v[88:89]
	v_cvt_pk_bf16_f32 v85, v86, v87
	v_and_b32_e32 v115, 0xffff0000, v237
	v_cvt_pk_bf16_f32 v84, v90, v91
	v_lshlrev_b32_e32 v94, 16, v85
	v_and_b32_e32 v89, 0xffff0000, v84
	v_sub_f32_e32 v89, v91, v89
	v_mul_f32_e32 v91, v91, v91
	v_fmac_f32_e32 v91, v90, v90
	v_lshlrev_b32_e32 v88, 16, v84
	v_and_b32_e32 v95, 0xffff0000, v85
	v_fmac_f32_e32 v91, v86, v86
	v_sub_f32_e32 v88, v90, v88
	v_sub_f32_e32 v94, v86, v94
	v_sub_f32_e32 v95, v87, v95
	v_fmac_f32_e32 v91, v87, v87
	v_cvt_pk_bf16_f32 v88, v88, v89
	v_cvt_pk_bf16_f32 v89, v94, v95
	v_add_f32_e32 v118, v128, v91
	v_lshlrev_b32_e32 v86, 16, v204
	v_lshlrev_b32_e32 v90, 16, v236
	v_and_b32_e32 v87, 0xffff0000, v204
	v_and_b32_e32 v91, 0xffff0000, v236
	v_lshlrev_b32_e32 v94, 16, v205
	v_and_b32_e32 v95, 0xffff0000, v205
	v_add_u32_e32 v247, 0x40000, v246
	global_load_dwordx4 v[194:197], v247, s[68:69]
	global_load_dwordx4 v[198:201], v247, s[88:89]
	global_load_dwordx4 v[202:205], v247, s[68:69] offset:64
	global_load_dwordx4 v[234:237], v247, s[88:89] offset:64
	v_pk_add_f32 v[86:87], v[86:87], v[90:91]
	v_pk_add_f32 v[90:91], v[94:95], v[114:115]
	v_pk_fma_f32 v[80:81], s[6:7], v[80:81], v[86:87]
	v_pk_fma_f32 v[82:83], s[60:61], v[82:83], v[90:91]
	v_cvt_pk_bf16_f32 v86, v80, v81
	v_lshl_add_u64 v[92:93], s[70:71], 0, v[148:149]
	v_and_b32_e32 v91, 0xffff0000, v86
	v_sub_f32_e32 v91, v81, v91
	v_mul_f32_e32 v81, v81, v81
	v_fmac_f32_e32 v81, v80, v80
	v_fmac_f32_e32 v81, v82, v82
	v_lshlrev_b32_e32 v90, 16, v86
	v_fmac_f32_e32 v81, v83, v83
	v_sub_f32_e32 v90, v80, v90
	v_add_f32_e32 v80, v118, v81
	v_mov_b32_e32 v81, v80
	s_nop 1
	v_permlane16_swap_b32_e32 v80, v81
	v_add_f32_e32 v80, v80, v81
	v_mov_b32_e32 v81, v80
	v_cvt_pk_bf16_f32 v87, v82, v83
	s_nop 1
	v_permlane32_swap_b32_e32 v80, v81
	v_lshlrev_b32_e32 v94, 16, v87
	v_and_b32_e32 v95, 0xffff0000, v87
	global_store_dwordx4 v[92:93], v[122:125], off
	v_sub_f32_e32 v94, v82, v94
	v_sub_f32_e32 v95, v83, v95
	v_cvt_pk_bf16_f32 v90, v90, v91
	v_cvt_pk_bf16_f32 v91, v94, v95
	global_store_dwordx4 v[126:127], v[84:87], off offset:64
	global_store_dwordx4 v[92:93], v[88:91], off offset:64
	s_and_saveexec_b64 s[36:37], s[0:1]
	s_cbranch_execz .LBB0_875
	v_add_f32_e32 v80, v80, v81
	global_atomic_add_f32 v[146:147], v80, off offset:128
; template <int EPI>
; __device__ __forceinline__ void gemm_epilogue(const f32x4 (&acc)[2][2][4][2], const Unit& u, int wr, int wc, int fr, int fq,
;                                               const EpiArgs& ea, const float (&rs_pre)[2][4]) {
;     ...
;       const int row = row0 + ai * 128 + m * 16;
;       float sq = 0.f;
; #pragma unroll
;       for (int bj = 0; bj < 2; ++bj) {
;         const size_t idx = (size_t)row * 1024 + lcp + bj * 32;
;         const uint32_t hw[4] = {hc[bj].x, hc[bj].y, hc[bj].z, hc[bj].w};
;         const uint32_t lw[4] = {lc[bj].x, lc[bj].y, lc[bj].z, lc[bj].w};
;         const uint32_t pw[4] = {pc[bj].x, pc[bj].y, pc[bj].z, pc[bj].w};
;         uint32_t ho[4], lo_[4];
; #pragma unroll
;         for (int n = 0; n < 2; ++n) {
;           f32x4 xv;
;           xv[0] = __uint_as_float(hw[2 * n] << 16) + __uint_as_float(lw[2 * n] << 16);
;           xv[1] = __uint_as_float(hw[2 * n] & 0xffff0000u) + __uint_as_float(lw[2 * n] & 0xffff0000u);
;           xv[2] = __uint_as_float(hw[2 * n + 1] << 16) + __uint_as_float(lw[2 * n + 1] << 16);
;           xv[3] = __uint_as_float(hw[2 * n + 1] & 0xffff0000u) + __uint_as_float(lw[2 * n + 1] & 0xffff0000u);
;           const f32x4 a = acc[ai][bj][m][n];
;           f32x4 v;
;           if constexpr (EPI == EPI_PLEGATE) {
;             const float rs = rsr[ai][m], rpe = rper[ai][m];
;             const float pv[4] = {__uint_as_float(pw[2 * n] << 16), __uint_as_float(pw[2 * n] & 0xffff0000u),
;                                  __uint_as_float(pw[2 * n + 1] << 16), __uint_as_float(pw[2 * n + 1] & 0xffff0000u)};
; #pragma unroll
;             for (int i = 0; i < 4; ++i) v[i] = xv[i] + sigmoidf_(a[i] * rs) * (pv[i] * rpe);
;           } else {
;             v = xv + a * ea.alpha;
;           }
;           const uint2 hnew = pack4(v);
;           ho[2 * n] = hnew.x; ho[2 * n + 1] = hnew.y;
;           if (ea.xf32_out) {
;             *reinterpret_cast<f32x4*>(ea.xf32_out + idx + 4 * n) = v;
;           } else {
;             f32x4 r;
;             r[0] = v[0] - __uint_as_float(hnew.x << 16);
;             r[1] = v[1] - __uint_as_float(hnew.x & 0xffff0000u);
;             r[2] = v[2] - __uint_as_float(hnew.y << 16);
;             r[3] = v[3] - __uint_as_float(hnew.y & 0xffff0000u);
;             const uint2 lnew = pack4(r);
;             lo_[2 * n] = lnew.x; lo_[2 * n + 1] = lnew.y;
;           }
.LBB0_875:
	s_waitcnt vmcnt(12)
	s_or_b64 exec, exec, s[36:37]
	v_add_u32_e32 v114, 0x80, v168
	v_ashrrev_i32_e32 v115, 31, v114
	v_lshlrev_b64 v[80:81], 10, v[114:115]
	v_lshl_add_u64 v[80:81], v[80:81], 0, v[166:167]
	v_lshlrev_b64 v[116:117], 1, v[80:81]
	v_lshl_add_u64 v[80:81], s[68:69], 0, v[116:117]
	v_lshl_add_u64 v[84:85], s[88:89], 0, v[116:117]
	s_nop 0
	s_nop 0
	s_nop 0
	v_lshlrev_b32_e32 v118, 16, v238
	v_lshlrev_b32_e32 v120, 16, v242
	v_and_b32_e32 v119, 0xffff0000, v238
	v_and_b32_e32 v121, 0xffff0000, v242
	v_lshlrev_b32_e32 v104, 16, v239
	v_lshlrev_b32_e32 v108, 16, v243
	v_and_b32_e32 v105, 0xffff0000, v239
	v_and_b32_e32 v109, 0xffff0000, v243
	v_pk_add_f32 v[118:119], v[118:119], v[120:121]
	v_pk_add_f32 v[104:105], v[104:105], v[108:109]
	v_pk_fma_f32 v[108:109], s[6:7], v[76:77], v[118:119]
	v_pk_fma_f32 v[78:79], s[60:61], v[78:79], v[104:105]
	v_cvt_pk_bf16_f32 v76, v108, v109
	s_nop 0
	v_cvt_pk_bf16_f32 v77, v78, v79
	v_lshlrev_b32_e32 v104, 16, v76
	v_and_b32_e32 v105, 0xffff0000, v76
	v_lshlrev_b32_e32 v115, 16, v77
	v_sub_f32_e32 v104, v108, v104
	v_sub_f32_e32 v105, v109, v105
	v_sub_f32_e32 v115, v78, v115
	v_and_b32_e32 v118, 0xffff0000, v77
	v_sub_f32_e32 v118, v79, v118
	v_cvt_pk_bf16_f32 v104, v104, v105
	v_cvt_pk_bf16_f32 v105, v115, v118
	v_mul_f32_e32 v115, v109, v109
	v_fmac_f32_e32 v115, v108, v108
	v_fmac_f32_e32 v115, v78, v78
	v_fmac_f32_e32 v115, v79, v79
	v_lshlrev_b32_e32 v78, 16, v240
	v_lshlrev_b32_e32 v108, 16, v244
	v_and_b32_e32 v79, 0xffff0000, v240
	v_and_b32_e32 v109, 0xffff0000, v244
	v_lshlrev_b32_e32 v106, 16, v241
	v_lshlrev_b32_e32 v110, 16, v245
	v_and_b32_e32 v107, 0xffff0000, v241
	v_and_b32_e32 v111, 0xffff0000, v245
	v_pk_add_f32 v[78:79], v[78:79], v[108:109]
	v_pk_add_f32 v[106:107], v[106:107], v[110:111]
	v_pk_fma_f32 v[72:73], s[6:7], v[72:73], v[78:79]
	v_pk_fma_f32 v[74:75], s[60:61], v[74:75], v[106:107]
	v_cvt_pk_bf16_f32 v78, v72, v73
	s_nop 0
	v_and_b32_e32 v107, 0xffff0000, v78
	v_sub_f32_e32 v107, v73, v107
	v_mul_f32_e32 v73, v73, v73
	v_cvt_pk_bf16_f32 v79, v74, v75
	v_lshlrev_b32_e32 v106, 16, v78
	v_lshlrev_b32_e32 v108, 16, v79
	v_and_b32_e32 v109, 0xffff0000, v79
	v_fmac_f32_e32 v73, v72, v72
	v_sub_f32_e32 v106, v72, v106
	v_sub_f32_e32 v108, v74, v108
	v_sub_f32_e32 v109, v75, v109
	v_fmac_f32_e32 v73, v74, v74
	v_cvt_pk_bf16_f32 v106, v106, v107
	v_cvt_pk_bf16_f32 v107, v108, v109
	v_fmac_f32_e32 v73, v75, v75
	v_lshl_add_u64 v[108:109], s[46:47], 0, v[130:131]
	v_add_f32_e32 v110, v115, v73
	global_store_dwordx4 v[108:109], v[76:79], off
	v_lshlrev_b32_e32 v72, 16, v210
	v_lshlrev_b32_e32 v74, 16, v214
	v_and_b32_e32 v73, 0xffff0000, v210
	v_and_b32_e32 v75, 0xffff0000, v214
	v_lshlrev_b32_e32 v78, 16, v211
	v_lshlrev_b32_e32 v96, 16, v215
	v_and_b32_e32 v79, 0xffff0000, v211
	v_and_b32_e32 v97, 0xffff0000, v215
	v_pk_add_f32 v[72:73], v[72:73], v[74:75]
	v_pk_add_f32 v[74:75], v[78:79], v[96:97]
	v_lshlrev_b32_e32 v96, 16, v217
	v_pk_fma_f32 v[70:71], s[60:61], v[70:71], v[74:75]
	v_pk_fma_f32 v[74:75], s[6:7], v[68:69], v[72:73]
	v_cvt_pk_bf16_f32 v69, v70, v71
	v_and_b32_e32 v97, 0xffff0000, v217
	v_cvt_pk_bf16_f32 v68, v74, v75
	v_lshlrev_b32_e32 v78, 16, v69
	v_and_b32_e32 v73, 0xffff0000, v68
	v_sub_f32_e32 v73, v75, v73
	v_mul_f32_e32 v75, v75, v75
	v_fmac_f32_e32 v75, v74, v74
	v_lshlrev_b32_e32 v72, 16, v68
	v_and_b32_e32 v79, 0xffff0000, v69
	v_fmac_f32_e32 v75, v70, v70
	v_sub_f32_e32 v72, v74, v72
	v_sub_f32_e32 v78, v70, v78
	v_sub_f32_e32 v79, v71, v79
	v_fmac_f32_e32 v75, v71, v71
	v_cvt_pk_bf16_f32 v72, v72, v73
	v_cvt_pk_bf16_f32 v73, v78, v79
	v_add_f32_e32 v100, v110, v75
	v_lshlrev_b32_e32 v70, 16, v212
	v_lshlrev_b32_e32 v74, 16, v216
	v_and_b32_e32 v71, 0xffff0000, v212
	v_and_b32_e32 v75, 0xffff0000, v216
	v_lshlrev_b32_e32 v78, 16, v213
	v_and_b32_e32 v79, 0xffff0000, v213
	v_add_u32_e32 v247, 0x48000, v246
	global_load_dwordx4 v[238:241], v247, s[68:69]
	global_load_dwordx4 v[242:245], v247, s[88:89]
	global_load_dwordx4 v[210:213], v247, s[68:69] offset:64
	global_load_dwordx4 v[214:217], v247, s[88:89] offset:64
	v_pk_add_f32 v[70:71], v[70:71], v[74:75]
	v_pk_add_f32 v[74:75], v[78:79], v[96:97]
	v_pk_fma_f32 v[64:65], s[6:7], v[64:65], v[70:71]
	v_pk_fma_f32 v[66:67], s[60:61], v[66:67], v[74:75]
	v_cvt_pk_bf16_f32 v70, v64, v65
	v_lshl_add_u64 v[76:77], s[70:71], 0, v[130:131]
	v_and_b32_e32 v75, 0xffff0000, v70
	v_sub_f32_e32 v75, v65, v75
	v_mul_f32_e32 v65, v65, v65
	v_fmac_f32_e32 v65, v64, v64
	v_fmac_f32_e32 v65, v66, v66
	v_lshlrev_b32_e32 v74, 16, v70
	v_fmac_f32_e32 v65, v67, v67
	v_sub_f32_e32 v74, v64, v74
	v_add_f32_e32 v64, v100, v65
	v_mov_b32_e32 v65, v64
	s_nop 1
	v_permlane16_swap_b32_e32 v64, v65
	v_add_f32_e32 v64, v64, v65
	v_mov_b32_e32 v65, v64
	v_cvt_pk_bf16_f32 v71, v66, v67
	s_nop 1
	v_permlane32_swap_b32_e32 v64, v65
	v_lshlrev_b32_e32 v78, 16, v71
	v_and_b32_e32 v79, 0xffff0000, v71
	global_store_dwordx4 v[76:77], v[104:107], off
	v_sub_f32_e32 v78, v66, v78
	v_sub_f32_e32 v79, v67, v79
	v_cvt_pk_bf16_f32 v74, v74, v75
	v_cvt_pk_bf16_f32 v75, v78, v79
	global_store_dwordx4 v[108:109], v[68:71], off offset:64
	global_store_dwordx4 v[76:77], v[72:75], off offset:64
	s_and_saveexec_b64 s[36:37], s[0:1]
	s_cbranch_execz .LBB0_877
	v_add_f32_e32 v64, v64, v65
	global_atomic_add_f32 v[146:147], v64, off offset:192
; template <int EPI>
; __device__ __forceinline__ void gemm_epilogue(const f32x4 (&acc)[2][2][4][2], const Unit& u, int wr, int wc, int fr, int fq,
;                                               const EpiArgs& ea, const float (&rs_pre)[2][4]) {
;     ...
;       const int row = row0 + ai * 128 + m * 16;
;       float sq = 0.f;
; #pragma unroll
;       for (int bj = 0; bj < 2; ++bj) {
;         const size_t idx = (size_t)row * 1024 + lcp + bj * 32;
;         const uint32_t hw[4] = {hc[bj].x, hc[bj].y, hc[bj].z, hc[bj].w};
;         const uint32_t lw[4] = {lc[bj].x, lc[bj].y, lc[bj].z, lc[bj].w};
;         const uint32_t pw[4] = {pc[bj].x, pc[bj].y, pc[bj].z, pc[bj].w};
;         uint32_t ho[4], lo_[4];
; #pragma unroll
;         for (int n = 0; n < 2; ++n) {
;           f32x4 xv;
;           xv[0] = __uint_as_float(hw[2 * n] << 16) + __uint_as_float(lw[2 * n] << 16);
;           xv[1] = __uint_as_float(hw[2 * n] & 0xffff0000u) + __uint_as_float(lw[2 * n] & 0xffff0000u);
;           xv[2] = __uint_as_float(hw[2 * n + 1] << 16) + __uint_as_float(lw[2 * n + 1] << 16);
;           xv[3] = __uint_as_float(hw[2 * n + 1] & 0xffff0000u) + __uint_as_float(lw[2 * n + 1] & 0xffff0000u);
;           const f32x4 a = acc[ai][bj][m][n];
;           f32x4 v;
;           if constexpr (EPI == EPI_PLEGATE) {
;             const float rs = rsr[ai][m], rpe = rper[ai][m];
;             const float pv[4] = {__uint_as_float(pw[2 * n] << 16), __uint_as_float(pw[2 * n] & 0xffff0000u),
;                                  __uint_as_float(pw[2 * n + 1] << 16), __uint_as_float(pw[2 * n + 1] & 0xffff0000u)};
; #pragma unroll
;             for (int i = 0; i < 4; ++i) v[i] = xv[i] + sigmoidf_(a[i] * rs) * (pv[i] * rpe);
;           } else {
;             v = xv + a * ea.alpha;
;           }
;           const uint2 hnew = pack4(v);
;           ho[2 * n] = hnew.x; ho[2 * n + 1] = hnew.y;
;           if (ea.xf32_out) {
;             *reinterpret_cast<f32x4*>(ea.xf32_out + idx + 4 * n) = v;
;           } else {
;             f32x4 r;
;             r[0] = v[0] - __uint_as_float(hnew.x << 16);
;             r[1] = v[1] - __uint_as_float(hnew.x & 0xffff0000u);
;             r[2] = v[2] - __uint_as_float(hnew.y << 16);
;             r[3] = v[3] - __uint_as_float(hnew.y & 0xffff0000u);
;             const uint2 lnew = pack4(r);
;             lo_[2 * n] = lnew.x; lo_[2 * n + 1] = lnew.y;
;           }
.LBB0_877:
	s_waitcnt vmcnt(12)
	s_or_b64 exec, exec, s[36:37]
	v_or_b32_e32 v64, 16, v114
	v_ashrrev_i32_e32 v65, 31, v64
	v_lshlrev_b64 v[64:65], 10, v[64:65]
	v_lshl_add_u64 v[64:65], v[64:65], 0, v[166:167]
	v_lshlrev_b64 v[96:97], 1, v[64:65]
	v_lshl_add_u64 v[64:65], s[68:69], 0, v[96:97]
	v_lshl_add_u64 v[68:69], s[88:89], 0, v[96:97]
	s_nop 0
	s_nop 0
	s_nop 0
	v_lshlrev_b32_e32 v98, 16, v194
	v_lshlrev_b32_e32 v100, 16, v198
	v_and_b32_e32 v99, 0xffff0000, v194
	v_and_b32_e32 v101, 0xffff0000, v198
	v_lshlrev_b32_e32 v88, 16, v195
	v_lshlrev_b32_e32 v92, 16, v199
	v_and_b32_e32 v89, 0xffff0000, v195
	v_and_b32_e32 v93, 0xffff0000, v199
	v_pk_add_f32 v[98:99], v[98:99], v[100:101]
	v_pk_add_f32 v[88:89], v[88:89], v[92:93]
	v_pk_fma_f32 v[92:93], s[6:7], v[60:61], v[98:99]
	v_pk_fma_f32 v[62:63], s[60:61], v[62:63], v[88:89]
	v_cvt_pk_bf16_f32 v60, v92, v93
	s_nop 0
	v_cvt_pk_bf16_f32 v61, v62, v63
	v_lshlrev_b32_e32 v88, 16, v60
	v_and_b32_e32 v89, 0xffff0000, v60
	v_lshlrev_b32_e32 v98, 16, v61
	v_sub_f32_e32 v88, v92, v88
	v_sub_f32_e32 v89, v93, v89
	v_sub_f32_e32 v98, v62, v98
	v_and_b32_e32 v99, 0xffff0000, v61
	v_sub_f32_e32 v99, v63, v99
	v_cvt_pk_bf16_f32 v88, v88, v89
	v_cvt_pk_bf16_f32 v89, v98, v99
	v_mul_f32_e32 v98, v93, v93
	v_fmac_f32_e32 v98, v92, v92
	v_fmac_f32_e32 v98, v62, v62
	v_fmac_f32_e32 v98, v63, v63
	v_lshlrev_b32_e32 v62, 16, v196
	v_lshlrev_b32_e32 v92, 16, v200
	v_and_b32_e32 v63, 0xffff0000, v196
	v_and_b32_e32 v93, 0xffff0000, v200
	v_lshlrev_b32_e32 v90, 16, v197
	v_lshlrev_b32_e32 v94, 16, v201
	v_and_b32_e32 v91, 0xffff0000, v197
	v_and_b32_e32 v95, 0xffff0000, v201
	v_pk_add_f32 v[62:63], v[62:63], v[92:93]
	v_pk_add_f32 v[90:91], v[90:91], v[94:95]
	v_pk_fma_f32 v[56:57], s[6:7], v[56:57], v[62:63]
	v_pk_fma_f32 v[58:59], s[60:61], v[58:59], v[90:91]
	v_cvt_pk_bf16_f32 v62, v56, v57
	s_nop 0
	v_and_b32_e32 v91, 0xffff0000, v62
	v_sub_f32_e32 v91, v57, v91
	v_mul_f32_e32 v57, v57, v57
	v_cvt_pk_bf16_f32 v63, v58, v59
	v_lshlrev_b32_e32 v90, 16, v62
	v_lshlrev_b32_e32 v92, 16, v63
	v_and_b32_e32 v93, 0xffff0000, v63
	v_fmac_f32_e32 v57, v56, v56
	v_sub_f32_e32 v90, v56, v90
	v_sub_f32_e32 v92, v58, v92
	v_sub_f32_e32 v93, v59, v93
	v_fmac_f32_e32 v57, v58, v58
	v_cvt_pk_bf16_f32 v90, v90, v91
	v_cvt_pk_bf16_f32 v91, v92, v93
	v_fmac_f32_e32 v57, v59, v59
	v_lshl_add_u64 v[92:93], s[46:47], 0, v[116:117]
	v_add_f32_e32 v94, v98, v57
	global_store_dwordx4 v[92:93], v[60:63], off
	v_lshlrev_b32_e32 v56, 16, v202
	v_lshlrev_b32_e32 v58, 16, v234
	v_and_b32_e32 v57, 0xffff0000, v202
	v_and_b32_e32 v59, 0xffff0000, v234
	v_lshlrev_b32_e32 v62, 16, v203
	v_lshlrev_b32_e32 v80, 16, v235
	v_and_b32_e32 v63, 0xffff0000, v203
	v_and_b32_e32 v81, 0xffff0000, v235
	v_pk_add_f32 v[56:57], v[56:57], v[58:59]
	v_pk_add_f32 v[58:59], v[62:63], v[80:81]
	v_lshlrev_b32_e32 v80, 16, v237
	v_pk_fma_f32 v[54:55], s[60:61], v[54:55], v[58:59]
	v_pk_fma_f32 v[58:59], s[6:7], v[52:53], v[56:57]
	v_cvt_pk_bf16_f32 v53, v54, v55
	v_and_b32_e32 v81, 0xffff0000, v237
	v_cvt_pk_bf16_f32 v52, v58, v59
	v_lshlrev_b32_e32 v62, 16, v53
	v_and_b32_e32 v57, 0xffff0000, v52
	v_sub_f32_e32 v57, v59, v57
	v_mul_f32_e32 v59, v59, v59
	v_fmac_f32_e32 v59, v58, v58
	v_lshlrev_b32_e32 v56, 16, v52
	v_and_b32_e32 v63, 0xffff0000, v53
	v_fmac_f32_e32 v59, v54, v54
	v_sub_f32_e32 v56, v58, v56
	v_sub_f32_e32 v62, v54, v62
	v_sub_f32_e32 v63, v55, v63
	v_fmac_f32_e32 v59, v55, v55
	v_cvt_pk_bf16_f32 v56, v56, v57
	v_cvt_pk_bf16_f32 v57, v62, v63
	v_add_f32_e32 v84, v94, v59
	v_lshlrev_b32_e32 v54, 16, v204
	v_lshlrev_b32_e32 v58, 16, v236
	v_and_b32_e32 v55, 0xffff0000, v204
	v_and_b32_e32 v59, 0xffff0000, v236
	v_lshlrev_b32_e32 v62, 16, v205
	v_and_b32_e32 v63, 0xffff0000, v205
	v_add_u32_e32 v247, 0x50000, v246
	global_load_dwordx4 v[194:197], v247, s[68:69]
	global_load_dwordx4 v[198:201], v247, s[88:89]
	global_load_dwordx4 v[202:205], v247, s[68:69] offset:64
	global_load_dwordx4 v[234:237], v247, s[88:89] offset:64
	v_pk_add_f32 v[54:55], v[54:55], v[58:59]
	v_pk_add_f32 v[58:59], v[62:63], v[80:81]
	v_pk_fma_f32 v[48:49], s[6:7], v[48:49], v[54:55]
	v_pk_fma_f32 v[50:51], s[60:61], v[50:51], v[58:59]
	v_cvt_pk_bf16_f32 v54, v48, v49
	v_lshl_add_u64 v[60:61], s[70:71], 0, v[116:117]
	v_and_b32_e32 v59, 0xffff0000, v54
	v_sub_f32_e32 v59, v49, v59
	v_mul_f32_e32 v49, v49, v49
	v_fmac_f32_e32 v49, v48, v48
	v_fmac_f32_e32 v49, v50, v50
	v_lshlrev_b32_e32 v58, 16, v54
	v_fmac_f32_e32 v49, v51, v51
	v_sub_f32_e32 v58, v48, v58
	v_add_f32_e32 v48, v84, v49
	v_mov_b32_e32 v49, v48
	s_nop 1
	v_permlane16_swap_b32_e32 v48, v49
	v_add_f32_e32 v48, v48, v49
	v_mov_b32_e32 v49, v48
	v_cvt_pk_bf16_f32 v55, v50, v51
	s_nop 1
	v_permlane32_swap_b32_e32 v48, v49
	v_lshlrev_b32_e32 v62, 16, v55
	v_and_b32_e32 v63, 0xffff0000, v55
	global_store_dwordx4 v[60:61], v[88:91], off
	v_sub_f32_e32 v62, v50, v62
	v_sub_f32_e32 v63, v51, v63
	v_cvt_pk_bf16_f32 v58, v58, v59
	v_cvt_pk_bf16_f32 v59, v62, v63
	global_store_dwordx4 v[92:93], v[52:55], off offset:64
	global_store_dwordx4 v[60:61], v[56:59], off offset:64
	s_and_saveexec_b64 s[36:37], s[0:1]
	s_cbranch_execz .LBB0_879
	v_add_f32_e32 v48, v48, v49
	global_atomic_add_f32 v[146:147], v48, off offset:512
; template <int EPI>
; __device__ __forceinline__ void gemm_epilogue(const f32x4 (&acc)[2][2][4][2], const Unit& u, int wr, int wc, int fr, int fq,
;                                               const EpiArgs& ea, const float (&rs_pre)[2][4]) {
;     ...
;       const int row = row0 + ai * 128 + m * 16;
;       float sq = 0.f;
; #pragma unroll
;       for (int bj = 0; bj < 2; ++bj) {
;         const size_t idx = (size_t)row * 1024 + lcp + bj * 32;
;         const uint32_t hw[4] = {hc[bj].x, hc[bj].y, hc[bj].z, hc[bj].w};
;         const uint32_t lw[4] = {lc[bj].x, lc[bj].y, lc[bj].z, lc[bj].w};
;         const uint32_t pw[4] = {pc[bj].x, pc[bj].y, pc[bj].z, pc[bj].w};
;         uint32_t ho[4], lo_[4];
; #pragma unroll
;         for (int n = 0; n < 2; ++n) {
;           f32x4 xv;
;           xv[0] = __uint_as_float(hw[2 * n] << 16) + __uint_as_float(lw[2 * n] << 16);
;           xv[1] = __uint_as_float(hw[2 * n] & 0xffff0000u) + __uint_as_float(lw[2 * n] & 0xffff0000u);
;           xv[2] = __uint_as_float(hw[2 * n + 1] << 16) + __uint_as_float(lw[2 * n + 1] << 16);
;           xv[3] = __uint_as_float(hw[2 * n + 1] & 0xffff0000u) + __uint_as_float(lw[2 * n + 1] & 0xffff0000u);
;           const f32x4 a = acc[ai][bj][m][n];
;           f32x4 v;
;           if constexpr (EPI == EPI_PLEGATE) {
;             const float rs = rsr[ai][m], rpe = rper[ai][m];
;             const float pv[4] = {__uint_as_float(pw[2 * n] << 16), __uint_as_float(pw[2 * n] & 0xffff0000u),
;                                  __uint_as_float(pw[2 * n + 1] << 16), __uint_as_float(pw[2 * n + 1] & 0xffff0000u)};
; #pragma unroll
;             for (int i = 0; i < 4; ++i) v[i] = xv[i] + sigmoidf_(a[i] * rs) * (pv[i] * rpe);
;           } else {
;             v = xv + a * ea.alpha;
;           }
;           const uint2 hnew = pack4(v);
;           ho[2 * n] = hnew.x; ho[2 * n + 1] = hnew.y;
;           if (ea.xf32_out) {
;             *reinterpret_cast<f32x4*>(ea.xf32_out + idx + 4 * n) = v;
;           } else {
;             f32x4 r;
;             r[0] = v[0] - __uint_as_float(hnew.x << 16);
;             r[1] = v[1] - __uint_as_float(hnew.x & 0xffff0000u);
;             r[2] = v[2] - __uint_as_float(hnew.y << 16);
;             r[3] = v[3] - __uint_as_float(hnew.y & 0xffff0000u);
;             const uint2 lnew = pack4(r);
;             lo_[2 * n] = lnew.x; lo_[2 * n + 1] = lnew.y;
;           }
.LBB0_879:
	s_waitcnt vmcnt(12)
	s_or_b64 exec, exec, s[36:37]
	v_or_b32_e32 v48, 32, v114
	v_ashrrev_i32_e32 v49, 31, v48
	v_lshlrev_b64 v[48:49], 10, v[48:49]
	v_lshl_add_u64 v[48:49], v[48:49], 0, v[166:167]
	v_lshlrev_b64 v[80:81], 1, v[48:49]
	v_lshl_add_u64 v[48:49], s[68:69], 0, v[80:81]
	v_lshl_add_u64 v[52:53], s[88:89], 0, v[80:81]
	s_nop 0
	s_nop 0
	s_nop 0
	v_lshlrev_b32_e32 v82, 16, v238
	v_lshlrev_b32_e32 v84, 16, v242
	v_and_b32_e32 v83, 0xffff0000, v238
	v_and_b32_e32 v85, 0xffff0000, v242
	v_lshlrev_b32_e32 v72, 16, v239
	v_lshlrev_b32_e32 v76, 16, v243
	v_and_b32_e32 v73, 0xffff0000, v239
	v_and_b32_e32 v77, 0xffff0000, v243
	v_pk_add_f32 v[82:83], v[82:83], v[84:85]
	v_pk_add_f32 v[72:73], v[72:73], v[76:77]
	v_pk_fma_f32 v[76:77], s[6:7], v[44:45], v[82:83]
	v_pk_fma_f32 v[46:47], s[60:61], v[46:47], v[72:73]
	v_cvt_pk_bf16_f32 v44, v76, v77
	s_nop 0
	v_cvt_pk_bf16_f32 v45, v46, v47
	v_lshlrev_b32_e32 v72, 16, v44
	v_and_b32_e32 v73, 0xffff0000, v44
	v_lshlrev_b32_e32 v82, 16, v45
	v_sub_f32_e32 v72, v76, v72
	v_sub_f32_e32 v73, v77, v73
	v_sub_f32_e32 v82, v46, v82
	v_and_b32_e32 v83, 0xffff0000, v45
	v_sub_f32_e32 v83, v47, v83
	v_cvt_pk_bf16_f32 v72, v72, v73
	v_cvt_pk_bf16_f32 v73, v82, v83
	v_mul_f32_e32 v82, v77, v77
	v_fmac_f32_e32 v82, v76, v76
	v_fmac_f32_e32 v82, v46, v46
	v_fmac_f32_e32 v82, v47, v47
	v_lshlrev_b32_e32 v46, 16, v240
	v_lshlrev_b32_e32 v76, 16, v244
	v_and_b32_e32 v47, 0xffff0000, v240
	v_and_b32_e32 v77, 0xffff0000, v244
	v_lshlrev_b32_e32 v74, 16, v241
	v_lshlrev_b32_e32 v78, 16, v245
	v_and_b32_e32 v75, 0xffff0000, v241
	v_and_b32_e32 v79, 0xffff0000, v245
	v_pk_add_f32 v[46:47], v[46:47], v[76:77]
	v_pk_add_f32 v[74:75], v[74:75], v[78:79]
	v_pk_fma_f32 v[40:41], s[6:7], v[40:41], v[46:47]
	v_pk_fma_f32 v[42:43], s[60:61], v[42:43], v[74:75]
	v_cvt_pk_bf16_f32 v46, v40, v41
	s_nop 0
	v_and_b32_e32 v75, 0xffff0000, v46
	v_sub_f32_e32 v75, v41, v75
	v_mul_f32_e32 v41, v41, v41
	v_cvt_pk_bf16_f32 v47, v42, v43
	v_lshlrev_b32_e32 v74, 16, v46
	v_lshlrev_b32_e32 v76, 16, v47
	v_and_b32_e32 v77, 0xffff0000, v47
	v_fmac_f32_e32 v41, v40, v40
	v_sub_f32_e32 v74, v40, v74
	v_sub_f32_e32 v76, v42, v76
	v_sub_f32_e32 v77, v43, v77
	v_fmac_f32_e32 v41, v42, v42
	v_cvt_pk_bf16_f32 v74, v74, v75
	v_cvt_pk_bf16_f32 v75, v76, v77
	v_fmac_f32_e32 v41, v43, v43
	v_lshl_add_u64 v[76:77], s[46:47], 0, v[96:97]
	v_add_f32_e32 v78, v82, v41
	global_store_dwordx4 v[76:77], v[44:47], off
	v_lshlrev_b32_e32 v40, 16, v210
	v_lshlrev_b32_e32 v42, 16, v214
	v_and_b32_e32 v41, 0xffff0000, v210
	v_and_b32_e32 v43, 0xffff0000, v214
	v_lshlrev_b32_e32 v46, 16, v211
	v_lshlrev_b32_e32 v64, 16, v215
	v_and_b32_e32 v47, 0xffff0000, v211
	v_and_b32_e32 v65, 0xffff0000, v215
	v_pk_add_f32 v[40:41], v[40:41], v[42:43]
	v_pk_add_f32 v[42:43], v[46:47], v[64:65]
	v_lshlrev_b32_e32 v64, 16, v217
	v_pk_fma_f32 v[38:39], s[60:61], v[38:39], v[42:43]
	v_pk_fma_f32 v[42:43], s[6:7], v[36:37], v[40:41]
	v_cvt_pk_bf16_f32 v37, v38, v39
	v_and_b32_e32 v65, 0xffff0000, v217
	v_cvt_pk_bf16_f32 v36, v42, v43
	v_lshlrev_b32_e32 v46, 16, v37
	v_and_b32_e32 v41, 0xffff0000, v36
	v_sub_f32_e32 v41, v43, v41
	v_mul_f32_e32 v43, v43, v43
	v_fmac_f32_e32 v43, v42, v42
	v_lshlrev_b32_e32 v40, 16, v36
	v_and_b32_e32 v47, 0xffff0000, v37
	v_fmac_f32_e32 v43, v38, v38
	v_sub_f32_e32 v40, v42, v40
	v_sub_f32_e32 v46, v38, v46
	v_sub_f32_e32 v47, v39, v47
	v_fmac_f32_e32 v43, v39, v39
	v_cvt_pk_bf16_f32 v40, v40, v41
	v_cvt_pk_bf16_f32 v41, v46, v47
	v_add_f32_e32 v68, v78, v43
	v_lshlrev_b32_e32 v38, 16, v212
	v_lshlrev_b32_e32 v42, 16, v216
	v_and_b32_e32 v39, 0xffff0000, v212
	v_and_b32_e32 v43, 0xffff0000, v216
	v_lshlrev_b32_e32 v46, 16, v213
	v_and_b32_e32 v47, 0xffff0000, v213
	v_add_u32_e32 v247, 0x58000, v246
	global_load_dwordx4 v[238:241], v247, s[68:69]
	global_load_dwordx4 v[242:245], v247, s[88:89]
	global_load_dwordx4 v[210:213], v247, s[68:69] offset:64
	global_load_dwordx4 v[214:217], v247, s[88:89] offset:64
	v_pk_add_f32 v[38:39], v[38:39], v[42:43]
	v_pk_add_f32 v[42:43], v[46:47], v[64:65]
	v_pk_fma_f32 v[32:33], s[6:7], v[32:33], v[38:39]
	v_pk_fma_f32 v[34:35], s[60:61], v[34:35], v[42:43]
	v_cvt_pk_bf16_f32 v38, v32, v33
	v_lshl_add_u64 v[44:45], s[70:71], 0, v[96:97]
	v_and_b32_e32 v43, 0xffff0000, v38
	v_sub_f32_e32 v43, v33, v43
	v_mul_f32_e32 v33, v33, v33
	v_fmac_f32_e32 v33, v32, v32
	v_fmac_f32_e32 v33, v34, v34
	v_lshlrev_b32_e32 v42, 16, v38
	v_fmac_f32_e32 v33, v35, v35
	v_sub_f32_e32 v42, v32, v42
	v_add_f32_e32 v32, v68, v33
	v_mov_b32_e32 v33, v32
	s_nop 1
	v_permlane16_swap_b32_e32 v32, v33
	v_add_f32_e32 v32, v32, v33
	v_mov_b32_e32 v33, v32
	v_cvt_pk_bf16_f32 v39, v34, v35
	s_nop 1
	v_permlane32_swap_b32_e32 v32, v33
	v_lshlrev_b32_e32 v46, 16, v39
	v_and_b32_e32 v47, 0xffff0000, v39
	global_store_dwordx4 v[44:45], v[72:75], off
	v_sub_f32_e32 v46, v34, v46
	v_sub_f32_e32 v47, v35, v47
	v_cvt_pk_bf16_f32 v42, v42, v43
	v_cvt_pk_bf16_f32 v43, v46, v47
	global_store_dwordx4 v[76:77], v[36:39], off offset:64
	global_store_dwordx4 v[44:45], v[40:43], off offset:64
	s_and_saveexec_b64 s[36:37], s[0:1]
	s_cbranch_execz .LBB0_881
	v_add_f32_e32 v32, v32, v33
	global_atomic_add_f32 v[146:147], v32, off offset:576
; template <int EPI>
; __device__ __forceinline__ void gemm_epilogue(const f32x4 (&acc)[2][2][4][2], const Unit& u, int wr, int wc, int fr, int fq,
;                                               const EpiArgs& ea, const float (&rs_pre)[2][4]) {
;     ...
;       const int row = row0 + ai * 128 + m * 16;
;       float sq = 0.f;
; #pragma unroll
;       for (int bj = 0; bj < 2; ++bj) {
;         const size_t idx = (size_t)row * 1024 + lcp + bj * 32;
;         const uint32_t hw[4] = {hc[bj].x, hc[bj].y, hc[bj].z, hc[bj].w};
;         const uint32_t lw[4] = {lc[bj].x, lc[bj].y, lc[bj].z, lc[bj].w};
;         const uint32_t pw[4] = {pc[bj].x, pc[bj].y, pc[bj].z, pc[bj].w};
;         uint32_t ho[4], lo_[4];
; #pragma unroll
;         for (int n = 0; n < 2; ++n) {
;           f32x4 xv;
;           xv[0] = __uint_as_float(hw[2 * n] << 16) + __uint_as_float(lw[2 * n] << 16);
;           xv[1] = __uint_as_float(hw[2 * n] & 0xffff0000u) + __uint_as_float(lw[2 * n] & 0xffff0000u);
;           xv[2] = __uint_as_float(hw[2 * n + 1] << 16) + __uint_as_float(lw[2 * n + 1] << 16);
;           xv[3] = __uint_as_float(hw[2 * n + 1] & 0xffff0000u) + __uint_as_float(lw[2 * n + 1] & 0xffff0000u);
;           const f32x4 a = acc[ai][bj][m][n];
;           f32x4 v;
;           if constexpr (EPI == EPI_PLEGATE) {
;             const float rs = rsr[ai][m], rpe = rper[ai][m];
;             const float pv[4] = {__uint_as_float(pw[2 * n] << 16), __uint_as_float(pw[2 * n] & 0xffff0000u),
;                                  __uint_as_float(pw[2 * n + 1] << 16), __uint_as_float(pw[2 * n + 1] & 0xffff0000u)};
; #pragma unroll
;             for (int i = 0; i < 4; ++i) v[i] = xv[i] + sigmoidf_(a[i] * rs) * (pv[i] * rpe);
;           } else {
;             v = xv + a * ea.alpha;
;           }
;           const uint2 hnew = pack4(v);
;           ho[2 * n] = hnew.x; ho[2 * n + 1] = hnew.y;
;           if (ea.xf32_out) {
;             *reinterpret_cast<f32x4*>(ea.xf32_out + idx + 4 * n) = v;
;           } else {
;             f32x4 r;
;             r[0] = v[0] - __uint_as_float(hnew.x << 16);
;             r[1] = v[1] - __uint_as_float(hnew.x & 0xffff0000u);
;             r[2] = v[2] - __uint_as_float(hnew.y << 16);
;             r[3] = v[3] - __uint_as_float(hnew.y & 0xffff0000u);
;             const uint2 lnew = pack4(r);
;             lo_[2 * n] = lnew.x; lo_[2 * n + 1] = lnew.y;
;           }
.LBB0_881:
	s_waitcnt vmcnt(12)
	s_or_b64 exec, exec, s[36:37]
	v_or_b32_e32 v32, 48, v114
	v_ashrrev_i32_e32 v33, 31, v32
	v_lshlrev_b64 v[32:33], 10, v[32:33]
	v_lshl_add_u64 v[32:33], v[32:33], 0, v[166:167]
	v_lshlrev_b64 v[64:65], 1, v[32:33]
	v_lshl_add_u64 v[32:33], s[68:69], 0, v[64:65]
	v_lshl_add_u64 v[36:37], s[88:89], 0, v[64:65]
	s_nop 0
	s_nop 0
	s_nop 0
	v_lshlrev_b32_e32 v66, 16, v194
	v_lshlrev_b32_e32 v68, 16, v198
	v_and_b32_e32 v67, 0xffff0000, v194
	v_and_b32_e32 v69, 0xffff0000, v198
	v_lshlrev_b32_e32 v56, 16, v195
	v_lshlrev_b32_e32 v60, 16, v199
	v_and_b32_e32 v57, 0xffff0000, v195
	v_and_b32_e32 v61, 0xffff0000, v199
	v_pk_add_f32 v[66:67], v[66:67], v[68:69]
	v_pk_add_f32 v[56:57], v[56:57], v[60:61]
	v_pk_fma_f32 v[60:61], s[6:7], v[28:29], v[66:67]
	v_pk_fma_f32 v[30:31], s[60:61], v[30:31], v[56:57]
	v_cvt_pk_bf16_f32 v28, v60, v61
	s_nop 0
	v_cvt_pk_bf16_f32 v29, v30, v31
	v_lshlrev_b32_e32 v56, 16, v28
	v_and_b32_e32 v57, 0xffff0000, v28
	v_lshlrev_b32_e32 v66, 16, v29
	v_sub_f32_e32 v56, v60, v56
	v_sub_f32_e32 v57, v61, v57
	v_sub_f32_e32 v66, v30, v66
	v_and_b32_e32 v67, 0xffff0000, v29
	v_sub_f32_e32 v67, v31, v67
	v_cvt_pk_bf16_f32 v56, v56, v57
	v_cvt_pk_bf16_f32 v57, v66, v67
	v_mul_f32_e32 v66, v61, v61
	v_fmac_f32_e32 v66, v60, v60
	v_fmac_f32_e32 v66, v30, v30
	v_fmac_f32_e32 v66, v31, v31
	v_lshlrev_b32_e32 v30, 16, v196
	v_lshlrev_b32_e32 v60, 16, v200
	v_and_b32_e32 v31, 0xffff0000, v196
	v_and_b32_e32 v61, 0xffff0000, v200
	v_lshlrev_b32_e32 v58, 16, v197
	v_lshlrev_b32_e32 v62, 16, v201
	v_and_b32_e32 v59, 0xffff0000, v197
	v_and_b32_e32 v63, 0xffff0000, v201
	v_pk_add_f32 v[30:31], v[30:31], v[60:61]
	v_pk_add_f32 v[58:59], v[58:59], v[62:63]
	v_pk_fma_f32 v[24:25], s[6:7], v[24:25], v[30:31]
	v_pk_fma_f32 v[26:27], s[60:61], v[26:27], v[58:59]
	v_cvt_pk_bf16_f32 v30, v24, v25
	s_nop 0
	v_and_b32_e32 v59, 0xffff0000, v30
	v_sub_f32_e32 v59, v25, v59
	v_mul_f32_e32 v25, v25, v25
	v_cvt_pk_bf16_f32 v31, v26, v27
	v_lshlrev_b32_e32 v58, 16, v30
	v_lshlrev_b32_e32 v60, 16, v31
	v_and_b32_e32 v61, 0xffff0000, v31
	v_fmac_f32_e32 v25, v24, v24
	v_sub_f32_e32 v58, v24, v58
	v_sub_f32_e32 v60, v26, v60
	v_sub_f32_e32 v61, v27, v61
	v_fmac_f32_e32 v25, v26, v26
	v_cvt_pk_bf16_f32 v58, v58, v59
	v_cvt_pk_bf16_f32 v59, v60, v61
	v_fmac_f32_e32 v25, v27, v27
	v_lshl_add_u64 v[60:61], s[46:47], 0, v[80:81]
	v_add_f32_e32 v62, v66, v25
	global_store_dwordx4 v[60:61], v[28:31], off
	v_lshlrev_b32_e32 v24, 16, v202
	v_lshlrev_b32_e32 v26, 16, v234
	v_and_b32_e32 v25, 0xffff0000, v202
	v_and_b32_e32 v27, 0xffff0000, v234
	v_lshlrev_b32_e32 v30, 16, v203
	v_lshlrev_b32_e32 v48, 16, v235
	v_and_b32_e32 v31, 0xffff0000, v203
	v_and_b32_e32 v49, 0xffff0000, v235
	v_pk_add_f32 v[24:25], v[24:25], v[26:27]
	v_pk_add_f32 v[26:27], v[30:31], v[48:49]
	v_lshlrev_b32_e32 v48, 16, v237
	v_pk_fma_f32 v[22:23], s[60:61], v[22:23], v[26:27]
	v_pk_fma_f32 v[26:27], s[6:7], v[20:21], v[24:25]
	v_cvt_pk_bf16_f32 v21, v22, v23
	v_and_b32_e32 v49, 0xffff0000, v237
	v_cvt_pk_bf16_f32 v20, v26, v27
	v_lshlrev_b32_e32 v30, 16, v21
	v_and_b32_e32 v25, 0xffff0000, v20
	v_sub_f32_e32 v25, v27, v25
	v_mul_f32_e32 v27, v27, v27
	v_fmac_f32_e32 v27, v26, v26
	v_lshlrev_b32_e32 v24, 16, v20
	v_and_b32_e32 v31, 0xffff0000, v21
	v_fmac_f32_e32 v27, v22, v22
	v_sub_f32_e32 v24, v26, v24
	v_sub_f32_e32 v30, v22, v30
	v_sub_f32_e32 v31, v23, v31
	v_fmac_f32_e32 v27, v23, v23
	v_cvt_pk_bf16_f32 v24, v24, v25
	v_cvt_pk_bf16_f32 v25, v30, v31
	v_add_f32_e32 v52, v62, v27
	v_lshlrev_b32_e32 v22, 16, v204
	v_lshlrev_b32_e32 v26, 16, v236
	v_and_b32_e32 v23, 0xffff0000, v204
	v_and_b32_e32 v27, 0xffff0000, v236
	v_lshlrev_b32_e32 v30, 16, v205
	v_and_b32_e32 v31, 0xffff0000, v205
	v_pk_add_f32 v[22:23], v[22:23], v[26:27]
	v_pk_add_f32 v[26:27], v[30:31], v[48:49]
	v_pk_fma_f32 v[16:17], s[6:7], v[16:17], v[22:23]
	v_pk_fma_f32 v[18:19], s[60:61], v[18:19], v[26:27]
	v_cvt_pk_bf16_f32 v22, v16, v17
	v_lshl_add_u64 v[28:29], s[70:71], 0, v[80:81]
	v_and_b32_e32 v27, 0xffff0000, v22
	v_sub_f32_e32 v27, v17, v27
	v_mul_f32_e32 v17, v17, v17
	v_fmac_f32_e32 v17, v16, v16
	v_fmac_f32_e32 v17, v18, v18
	v_lshlrev_b32_e32 v26, 16, v22
	v_fmac_f32_e32 v17, v19, v19
	v_sub_f32_e32 v26, v16, v26
	v_add_f32_e32 v16, v52, v17
	v_mov_b32_e32 v17, v16
	s_nop 1
	v_permlane16_swap_b32_e32 v16, v17
	v_add_f32_e32 v16, v16, v17
	v_mov_b32_e32 v17, v16
	v_cvt_pk_bf16_f32 v23, v18, v19
	s_nop 1
	v_permlane32_swap_b32_e32 v16, v17
	v_lshlrev_b32_e32 v30, 16, v23
	v_and_b32_e32 v31, 0xffff0000, v23
	global_store_dwordx4 v[28:29], v[56:59], off
	v_sub_f32_e32 v30, v18, v30
	v_sub_f32_e32 v31, v19, v31
	v_cvt_pk_bf16_f32 v26, v26, v27
	v_cvt_pk_bf16_f32 v27, v30, v31
	global_store_dwordx4 v[60:61], v[20:23], off offset:64
	global_store_dwordx4 v[28:29], v[24:27], off offset:64
	s_and_saveexec_b64 s[36:37], s[0:1]
	s_cbranch_execz .LBB0_883
	v_add_f32_e32 v16, v16, v17
	global_atomic_add_f32 v[146:147], v16, off offset:640
; template <int EPI>
; __device__ __forceinline__ void gemm_epilogue(const f32x4 (&acc)[2][2][4][2], const Unit& u, int wr, int wc, int fr, int fq,
;                                               const EpiArgs& ea, const float (&rs_pre)[2][4]) {
;     ...
;       const int row = row0 + ai * 128 + m * 16;
;       float sq = 0.f;
; #pragma unroll
;       for (int bj = 0; bj < 2; ++bj) {
;         const size_t idx = (size_t)row * 1024 + lcp + bj * 32;
;         const uint32_t hw[4] = {hc[bj].x, hc[bj].y, hc[bj].z, hc[bj].w};
;         const uint32_t lw[4] = {lc[bj].x, lc[bj].y, lc[bj].z, lc[bj].w};
;         const uint32_t pw[4] = {pc[bj].x, pc[bj].y, pc[bj].z, pc[bj].w};
;         uint32_t ho[4], lo_[4];
; #pragma unroll
;         for (int n = 0; n < 2; ++n) {
;           f32x4 xv;
;           xv[0] = __uint_as_float(hw[2 * n] << 16) + __uint_as_float(lw[2 * n] << 16);
;           xv[1] = __uint_as_float(hw[2 * n] & 0xffff0000u) + __uint_as_float(lw[2 * n] & 0xffff0000u);
;           xv[2] = __uint_as_float(hw[2 * n + 1] << 16) + __uint_as_float(lw[2 * n + 1] << 16);
;           xv[3] = __uint_as_float(hw[2 * n + 1] & 0xffff0000u) + __uint_as_float(lw[2 * n + 1] & 0xffff0000u);
;           const f32x4 a = acc[ai][bj][m][n];
;           f32x4 v;
;           if constexpr (EPI == EPI_PLEGATE) {
;             const float rs = rsr[ai][m], rpe = rper[ai][m];
;             const float pv[4] = {__uint_as_float(pw[2 * n] << 16), __uint_as_float(pw[2 * n] & 0xffff0000u),
;                                  __uint_as_float(pw[2 * n + 1] << 16), __uint_as_float(pw[2 * n + 1] & 0xffff0000u)};
; #pragma unroll
;             for (int i = 0; i < 4; ++i) v[i] = xv[i] + sigmoidf_(a[i] * rs) * (pv[i] * rpe);
;           } else {
;             v = xv + a * ea.alpha;
;           }
;           const uint2 hnew = pack4(v);
;           ho[2 * n] = hnew.x; ho[2 * n + 1] = hnew.y;
;           if (ea.xf32_out) {
;             *reinterpret_cast<f32x4*>(ea.xf32_out + idx + 4 * n) = v;
;           } else {
;             f32x4 r;
;             r[0] = v[0] - __uint_as_float(hnew.x << 16);
;             r[1] = v[1] - __uint_as_float(hnew.x & 0xffff0000u);
;             r[2] = v[2] - __uint_as_float(hnew.y << 16);
;             r[3] = v[3] - __uint_as_float(hnew.y & 0xffff0000u);
;             const uint2 lnew = pack4(r);
;             lo_[2 * n] = lnew.x; lo_[2 * n + 1] = lnew.y;
;           }
.LBB0_883:
	s_waitcnt vmcnt(8)
	s_or_b64 exec, exec, s[36:37]
	v_lshlrev_b32_e32 v16, 16, v238
	v_lshlrev_b32_e32 v18, 16, v242
	v_and_b32_e32 v17, 0xffff0000, v238
	v_and_b32_e32 v19, 0xffff0000, v242
	v_lshlrev_b32_e32 v20, 16, v239
	v_lshlrev_b32_e32 v22, 16, v243
	v_and_b32_e32 v21, 0xffff0000, v239
	v_and_b32_e32 v23, 0xffff0000, v243
	v_pk_add_f32 v[16:17], v[16:17], v[18:19]
	v_pk_add_f32 v[18:19], v[20:21], v[22:23]
	v_lshlrev_b32_e32 v22, 16, v245
	v_pk_fma_f32 v[14:15], s[60:61], v[14:15], v[18:19]
	v_pk_fma_f32 v[18:19], s[6:7], v[12:13], v[16:17]
	v_cvt_pk_bf16_f32 v13, v14, v15
	v_and_b32_e32 v23, 0xffff0000, v245
	v_mul_f32_e32 v24, v19, v19
	v_cvt_pk_bf16_f32 v12, v18, v19
	v_lshlrev_b32_e32 v20, 16, v13
	v_lshlrev_b32_e32 v16, 16, v12
	v_and_b32_e32 v17, 0xffff0000, v12
	v_and_b32_e32 v21, 0xffff0000, v13
	v_fmac_f32_e32 v24, v18, v18
	v_sub_f32_e32 v16, v18, v16
	v_sub_f32_e32 v17, v19, v17
	v_sub_f32_e32 v20, v14, v20
	v_sub_f32_e32 v21, v15, v21
	v_fmac_f32_e32 v24, v14, v14
	v_cvt_pk_bf16_f32 v16, v16, v17
	v_cvt_pk_bf16_f32 v17, v20, v21
	v_fmac_f32_e32 v24, v15, v15
	v_lshlrev_b32_e32 v14, 16, v240
	v_lshlrev_b32_e32 v18, 16, v244
	v_and_b32_e32 v15, 0xffff0000, v240
	v_and_b32_e32 v19, 0xffff0000, v244
	v_lshlrev_b32_e32 v20, 16, v241
	v_and_b32_e32 v21, 0xffff0000, v241
	v_pk_add_f32 v[14:15], v[14:15], v[18:19]
	v_pk_add_f32 v[18:19], v[20:21], v[22:23]
	v_pk_fma_f32 v[8:9], s[6:7], v[8:9], v[14:15]
	v_pk_fma_f32 v[10:11], s[60:61], v[10:11], v[18:19]
	v_cvt_pk_bf16_f32 v14, v8, v9
	s_nop 0
	v_and_b32_e32 v19, 0xffff0000, v14
	v_cvt_pk_bf16_f32 v15, v10, v11
	v_lshlrev_b32_e32 v18, 16, v14
	v_sub_f32_e32 v19, v9, v19
	v_lshlrev_b32_e32 v20, 16, v15
	v_and_b32_e32 v21, 0xffff0000, v15
	v_mul_f32_e32 v9, v9, v9
	v_sub_f32_e32 v18, v8, v18
	v_sub_f32_e32 v20, v10, v20
	v_sub_f32_e32 v21, v11, v21
	v_fmac_f32_e32 v9, v8, v8
	v_cvt_pk_bf16_f32 v18, v18, v19
	v_cvt_pk_bf16_f32 v19, v20, v21
	v_fmac_f32_e32 v9, v10, v10
	v_lshl_add_u64 v[20:21], s[46:47], 0, v[64:65]
	v_fmac_f32_e32 v9, v11, v11
	global_store_dwordx4 v[20:21], v[12:15], off
	v_add_f32_e32 v22, v24, v9
	v_lshlrev_b32_e32 v8, 16, v210
	v_lshl_add_u64 v[12:13], s[70:71], 0, v[64:65]
	global_store_dwordx4 v[12:13], v[16:19], off
	v_lshlrev_b32_e32 v10, 16, v214
	v_and_b32_e32 v9, 0xffff0000, v210
	v_and_b32_e32 v11, 0xffff0000, v214
	v_lshlrev_b32_e32 v14, 16, v211
	v_lshlrev_b32_e32 v16, 16, v215
	v_and_b32_e32 v15, 0xffff0000, v211
	v_and_b32_e32 v17, 0xffff0000, v215
	v_pk_add_f32 v[8:9], v[8:9], v[10:11]
	v_pk_add_f32 v[10:11], v[14:15], v[16:17]
	v_lshlrev_b32_e32 v16, 16, v217
	v_pk_fma_f32 v[6:7], s[60:61], v[6:7], v[10:11]
	v_pk_fma_f32 v[10:11], s[6:7], v[4:5], v[8:9]
	v_cvt_pk_bf16_f32 v5, v6, v7
	v_and_b32_e32 v17, 0xffff0000, v217
	v_cvt_pk_bf16_f32 v4, v10, v11
	v_lshlrev_b32_e32 v14, 16, v5
	v_and_b32_e32 v9, 0xffff0000, v4
	v_sub_f32_e32 v9, v11, v9
	v_mul_f32_e32 v11, v11, v11
	v_fmac_f32_e32 v11, v10, v10
	v_lshlrev_b32_e32 v8, 16, v4
	v_and_b32_e32 v15, 0xffff0000, v5
	v_fmac_f32_e32 v11, v6, v6
	v_sub_f32_e32 v8, v10, v8
	v_sub_f32_e32 v14, v6, v14
	v_sub_f32_e32 v15, v7, v15
	v_fmac_f32_e32 v11, v7, v7
	v_cvt_pk_bf16_f32 v8, v8, v9
	v_cvt_pk_bf16_f32 v9, v14, v15
	v_add_f32_e32 v18, v22, v11
	v_lshlrev_b32_e32 v6, 16, v212
	v_lshlrev_b32_e32 v10, 16, v216
	v_and_b32_e32 v7, 0xffff0000, v212
	v_and_b32_e32 v11, 0xffff0000, v216
	v_lshlrev_b32_e32 v14, 16, v213
	v_and_b32_e32 v15, 0xffff0000, v213
	v_pk_add_f32 v[6:7], v[6:7], v[10:11]
	v_pk_add_f32 v[10:11], v[14:15], v[16:17]
	v_pk_fma_f32 v[0:1], s[6:7], v[0:1], v[6:7]
	v_pk_fma_f32 v[2:3], s[60:61], v[2:3], v[10:11]
	v_cvt_pk_bf16_f32 v6, v0, v1
	s_nop 0
	v_and_b32_e32 v11, 0xffff0000, v6
	v_sub_f32_e32 v11, v1, v11
	v_mul_f32_e32 v1, v1, v1
	v_fmac_f32_e32 v1, v0, v0
	v_fmac_f32_e32 v1, v2, v2
	v_lshlrev_b32_e32 v10, 16, v6
	v_fmac_f32_e32 v1, v3, v3
	v_sub_f32_e32 v10, v0, v10
	v_add_f32_e32 v0, v18, v1
	v_mov_b32_e32 v1, v0
	s_nop 1
	v_permlane16_swap_b32_e32 v0, v1
	v_add_f32_e32 v0, v0, v1
	v_mov_b32_e32 v1, v0
	v_cvt_pk_bf16_f32 v7, v2, v3
	s_nop 1
	v_permlane32_swap_b32_e32 v0, v1
	v_lshlrev_b32_e32 v14, 16, v7
	v_and_b32_e32 v15, 0xffff0000, v7
	v_sub_f32_e32 v14, v2, v14
	v_sub_f32_e32 v15, v3, v15
	v_cvt_pk_bf16_f32 v10, v10, v11
	v_cvt_pk_bf16_f32 v11, v14, v15
	global_store_dwordx4 v[20:21], v[4:7], off offset:64
	global_store_dwordx4 v[12:13], v[8:11], off offset:64
	s_and_saveexec_b64 s[36:37], s[0:1]
	s_cbranch_execz .LBB0_855
	v_add_f32_e32 v0, v0, v1
	global_atomic_add_f32 v[146:147], v0, off offset:704
	s_branch .LBB0_855
